# input-copy phase: the four row loads issued together with counted waits instead of one load per full vmcnt drain
# baseline (speedup 1.0000x reference)
.LBB0_563:
	v_lshl_add_u64 v[34:35], v[4:5], 0, v[148:149]
	s_waitcnt lgkmcnt(0)
	global_load_dwordx4 v[26:29], v[34:35], off
	global_load_dwordx4 v[30:33], v[34:35], off offset:1024
	global_load_dwordx4 v[38:41], v[34:35], off offset:2048
	global_load_dwordx4 v[46:49], v[34:35], off offset:3072
	v_lshl_add_u64 v[42:43], v[8:9], 0, v[148:149]
	s_waitcnt vmcnt(3)
	global_store_dwordx4 v[42:43], v[26:29], off
	v_mul_f32_e32 v25, v27, v27
	v_fmac_f32_e32 v25, v26, v26
	v_fmac_f32_e32 v25, v28, v28
	v_fmac_f32_e32 v25, v29, v29
	v_cvt_pk_bf16_f32 v26, v26, v27
	v_cvt_pk_bf16_f32 v27, v28, v29
	global_store_dwordx2 v[6:7], v[26:27], off offset:-1024
	s_waitcnt vmcnt(4)
	global_store_dwordx4 v[42:43], v[30:33], off offset:1024
	v_fmac_f32_e32 v25, v31, v31
	v_fmac_f32_e32 v25, v30, v30
	v_fmac_f32_e32 v25, v32, v32
	v_fmac_f32_e32 v25, v33, v33
	v_cvt_pk_bf16_f32 v30, v30, v31
	v_cvt_pk_bf16_f32 v31, v32, v33
	global_store_dwordx2 v[6:7], v[30:31], off offset:-512
	s_waitcnt vmcnt(5)
	global_store_dwordx4 v[42:43], v[38:41], off offset:2048
	v_fmac_f32_e32 v25, v39, v39
	v_fmac_f32_e32 v25, v38, v38
	v_fmac_f32_e32 v25, v40, v40
	v_fmac_f32_e32 v25, v41, v41
	v_cvt_pk_bf16_f32 v38, v38, v39
	v_cvt_pk_bf16_f32 v39, v40, v41
	global_store_dwordx2 v[6:7], v[38:39], off
	s_waitcnt vmcnt(6)
	global_store_dwordx4 v[42:43], v[46:49], off offset:3072
	v_fmac_f32_e32 v25, v47, v47
	v_fmac_f32_e32 v25, v46, v46
	v_fmac_f32_e32 v25, v48, v48
	v_fmac_f32_e32 v25, v49, v49
	v_cvt_pk_bf16_f32 v46, v46, v47
	v_cvt_pk_bf16_f32 v47, v48, v49
	global_store_dwordx2 v[6:7], v[46:47], off offset:512
	s_nop 0
	ds_bpermute_b32 v26, v18, v25
	s_waitcnt lgkmcnt(0)
	v_add_f32_e32 v25, v25, v26
	ds_bpermute_b32 v26, v19, v25
	s_waitcnt lgkmcnt(0)
	v_add_f32_e32 v25, v25, v26
	ds_bpermute_b32 v26, v20, v25
	s_waitcnt lgkmcnt(0)
	v_add_f32_e32 v25, v25, v26
	ds_bpermute_b32 v26, v21, v25
	s_waitcnt lgkmcnt(0)
	v_add_f32_e32 v25, v25, v26
	ds_bpermute_b32 v26, v22, v25
	s_waitcnt lgkmcnt(0)
	v_add_f32_e32 v25, v25, v26
	ds_bpermute_b32 v26, v23, v25
	s_and_saveexec_b64 s[6:7], vcc
	s_cbranch_execz .LBB0_562
	s_waitcnt lgkmcnt(0)
	v_add_f32_e32 v25, v25, v26
	v_cndmask_b32_e64 v25, 0, v25, s[4:5]
	global_store_dword v[2:3], v25, off
	s_branch .LBB0_562
